# cache-policy hint: nt on the write-once f32 output stores of the final LayerNorm
# speedup vs baseline: 1.0047x; 1.0047x over previous
; __device__ __forceinline__ void ln_row_f32(float* io, const float* g, const float* b, int lane) {
;     f32x4* xr = (f32x4*)io + lane;
;     f32x4 v[4]; float s = 0.f;
; #pragma unroll
;     for (int j = 0; j < 4; ++j) { v[j] = xr[64 * j]; s += (v[j].x + v[j].y) + (v[j].z + v[j].w); }
;     const float mean = wave_sum(s) * (1.f / D); float s2 = 0.f;
; #pragma unroll
;     for (int j = 0; j < 4; ++j) { v[j] = v[j] - mean; s2 += (v[j].x * v[j].x + v[j].y * v[j].y) + (v[j].z * v[j].z + v[j].w * v[j].w); }
;     const float rstd = rsqrtf(wave_sum(s2) * (1.f / D) + LN_EPS);
; #pragma unroll
;     for (int j = 0; j < 4; ++j) { const int c = (64 * j + lane) * 4; xr[64 * j] = v[j] * rstd * *(const f32x4*)(g + c) + *(const f32x4*)(b + c); }
; }
.Lfln_nopf:
	v_add_f32_e32 v40, v8, v9
	v_add_f32_e32 v42, v10, v11
	v_mov_b32_e32 v35, v0
	v_mov_b32_e32 v39, v1
	v_mov_b32_e32 v41, v2
	v_mov_b32_e32 v43, v3
	v_pk_add_f32 v[34:35], v[34:35], v[38:39]
	v_pk_add_f32 v[38:39], v[40:41], v[42:43]
	s_nop 0
	v_pk_add_f32 v[34:35], v[34:35], v[38:39]
	s_nop 0
	v_add_f32_e32 v34, v34, v35
	s_nop 1
	v_add_f32_dpp v35, v34, v34 quad_perm:[1,0,3,2] row_mask:0xf bank_mask:0xf
	s_nop 1
	v_add_f32_dpp v34, v35, v35 quad_perm:[2,3,0,1] row_mask:0xf bank_mask:0xf
	s_nop 1
	v_add_f32_dpp v35, v34, v34 row_half_mirror row_mask:0xf bank_mask:0xf
	s_nop 1
	v_add_f32_dpp v34, v35, v35 row_mirror row_mask:0xf bank_mask:0xf
	s_nop 0
	v_readlane_b32 s14, v34, 0
	v_readlane_b32 s15, v34, 16
	v_readlane_b32 s16, v34, 32
	v_readlane_b32 s17, v34, 48
	s_nop 1
	v_mov_b32_e32 v35, s15
	v_add_f32_e32 v35, s14, v35
	v_mov_b32_e32 v34, s17
	v_add_f32_e32 v34, s16, v34
	v_add_f32_e32 v36, v35, v34
	v_fmamk_f32 v13, v36, 0xba800000, v13
	v_fmamk_f32 v12, v36, 0xba800000, v12
	v_fmamk_f32 v15, v36, 0xba800000, v15
	v_fmac_f32_e32 v14, 0xba800000, v36
	v_pk_mul_f32 v[34:35], v[14:15], v[14:15]
	v_pk_mul_f32 v[38:39], v[12:13], v[12:13]
	v_fmamk_f32 v7, v36, 0xba800000, v7
	v_pk_mov_b32 v[40:41], v[38:39], v[34:35] op_sel:[1,0]
	v_mov_b32_e32 v39, v35
	v_pk_add_f32 v[34:35], v[40:41], v[38:39]
	v_fmamk_f32 v39, v36, 0xba800000, v5
	v_fmamk_f32 v38, v36, 0xba800000, v4
	v_fmac_f32_e32 v6, 0xba800000, v36
	v_pk_add_f32 v[40:41], v[34:35], v[34:35] op_sel_hi:[0,1]
	v_pk_mul_f32 v[4:5], v[6:7], v[6:7]
	v_pk_mul_f32 v[34:35], v[38:39], v[38:39]
	v_fmac_f32_e32 v10, 0xba800000, v36
	v_pk_mov_b32 v[42:43], v[34:35], v[4:5] op_sel:[1,0]
	v_mov_b32_e32 v35, v5
	v_pk_add_f32 v[4:5], v[42:43], v[34:35]
	v_fmamk_f32 v34, v36, 0xba800000, v8
	v_pk_add_f32 v[4:5], v[4:5], v[4:5] op_sel_hi:[0,1]
	v_fmamk_f32 v35, v36, 0xba800000, v9
	v_mul_f32_e32 v4, v34, v34
	v_fmamk_f32 v11, v36, 0xba800000, v11
	v_pk_fma_f32 v[42:43], v[34:35], v[34:35], v[4:5] op_sel_hi:[1,1,0]
	v_mul_f32_e32 v4, v10, v10
	v_pk_fma_f32 v[50:51], v[10:11], v[10:11], v[4:5] op_sel_hi:[1,1,0]
	v_fmamk_f32 v9, v36, 0xba800000, v3
	v_fmamk_f32 v8, v36, 0xba800000, v2
	v_fmamk_f32 v1, v36, 0xba800000, v1
	v_fmac_f32_e32 v0, 0xba800000, v36
	v_mul_f32_e32 v42, v0, v0
	v_mul_f32_e32 v50, v1, v1
	v_mul_f32_e32 v40, v8, v8
	v_mul_f32_e32 v4, v9, v9
	v_pk_add_f32 v[2:3], v[42:43], v[50:51]
	v_pk_add_f32 v[4:5], v[40:41], v[4:5]
	s_nop 0
	v_pk_add_f32 v[2:3], v[2:3], v[4:5]
	s_nop 0
	v_add_f32_e32 v2, v2, v3
	s_nop 1
	v_add_f32_dpp v3, v2, v2 quad_perm:[1,0,3,2] row_mask:0xf bank_mask:0xf
	s_nop 1
	v_add_f32_dpp v2, v3, v3 quad_perm:[2,3,0,1] row_mask:0xf bank_mask:0xf
	s_nop 1
	v_add_f32_dpp v3, v2, v2 row_half_mirror row_mask:0xf bank_mask:0xf
	s_nop 1
	v_add_f32_dpp v2, v3, v3 row_mirror row_mask:0xf bank_mask:0xf
	s_nop 0
	v_readlane_b32 s14, v2, 0
	v_readlane_b32 s15, v2, 16
	v_readlane_b32 s16, v2, 32
	v_readlane_b32 s17, v2, 48
	s_nop 1
	v_mov_b32_e32 v3, s15
	v_add_f32_e32 v3, s14, v3
	v_mov_b32_e32 v2, s17
	v_add_f32_e32 v2, s16, v2
	v_add_f32_e32 v2, v3, v2
	v_fmamk_f32 v2, v2, 0x3a800000, v173
	v_cmp_gt_f32_e32 vcc, s81, v2
	v_mul_f32_e32 v3, 0x4b800000, v2
	s_nop 0
	v_cndmask_b32_e32 v2, v2, v3, vcc
	v_rsq_f32_e32 v2, v2
	s_nop 0
	v_mul_f32_e32 v3, 0x45800000, v2
	v_cndmask_b32_e32 v36, v2, v3, vcc
	v_pk_mul_f32 v[40:41], v[12:13], v[36:37] op_sel_hi:[1,0]
	v_pk_mul_f32 v[42:43], v[14:15], v[36:37] op_sel_hi:[1,0]
	v_pk_mul_f32 v[6:7], v[6:7], v[36:37] op_sel_hi:[1,0]
	v_pk_mul_f32 v[38:39], v[38:39], v[36:37] op_sel_hi:[1,0]
	v_pk_mul_f32 v[8:9], v[8:9], v[36:37] op_sel_hi:[1,0]
	v_pk_fma_f32 v[4:5], v[182:183], v[42:43], v[186:187]
	v_pk_fma_f32 v[2:3], v[180:181], v[40:41], v[184:185]
	global_store_dwordx4 v[32:33], v[2:5], off offset:-2048 nt
	s_nop 1
	v_pk_fma_f32 v[2:3], v[188:189], v[38:39], v[192:193]
	v_pk_fma_f32 v[4:5], v[190:191], v[6:7], v[194:195]
	global_store_dwordx4 v[32:33], v[2:5], off offset:-1024 nt
	v_pk_mul_f32 v[6:7], v[10:11], v[36:37] op_sel_hi:[1,0]
	v_pk_mul_f32 v[14:15], v[34:35], v[36:37] op_sel_hi:[1,0]
	s_nop 0
	v_pk_fma_f32 v[4:5], v[198:199], v[6:7], v[202:203]
	v_pk_fma_f32 v[2:3], v[196:197], v[14:15], v[200:201]
	global_store_dwordx4 v[32:33], v[2:5], off nt
	v_pk_mul_f32 v[10:11], v[0:1], v[36:37] op_sel_hi:[1,0]
	s_nop 0
	v_pk_fma_f32 v[0:1], v[204:205], v[10:11], v[208:209]
	v_pk_fma_f32 v[2:3], v[206:207], v[8:9], v[210:211]
	global_store_dwordx4 v[32:33], v[0:3], off offset:1024 nt
	v_lshl_add_u64 v[32:33], v[32:33], 0, s[94:95]
	s_cbranch_scc0 .LBB0_748
	v_readlane_b32 s14, v255, 46
	v_readlane_b32 s15, v255, 47
	v_readlane_b32 s16, v255, 48
	v_readlane_b32 s17, v255, 49
	s_nop 1
